# mLSTM step 4: per-row 1/max(|den|,emt) computed once per wave into LDS at step start; h finalize reduced to packed mul + cvt + b16 stores (was 4 LDS vector reads + fma/max/rcp per value)
# baseline (speedup 1.0000x reference)
.Lmls_2:
	s_add_u32 s12, s74, s4
	s_addc_u32 s13, s75, s31
	s_waitcnt lgkmcnt(0)
	v_lshl_add_u64 v[64:65], s[12:13], 0, v[96:97]
	v_add_co_u32_e32 v66, vcc, 0xf000000, v64
	s_waitcnt lgkmcnt(0)
	s_barrier
	v_lshrrev_b32_e32 v218, 5, v168
	s_nop 0
	v_addc_co_u32_e32 v67, vcc, 0, v65, vcc
	v_mov_b64_e32 v[206:207], v[66:67]
	v_mov_b64_e32 v[204:205], v[66:67]
	v_add_co_u32_e32 v66, vcc, 0xf001000, v64
	v_lshlrev_b32_e32 v217, 4, v218
	s_nop 0
	v_addc_co_u32_e32 v67, vcc, 0, v65, vcc
	v_mov_b64_e32 v[202:203], v[66:67]
	v_mov_b64_e32 v[200:201], v[66:67]
	v_add_co_u32_e32 v66, vcc, 0xf002000, v64
	v_add_u32_e32 v208, 0, v217
	s_nop 0
	v_addc_co_u32_e32 v67, vcc, 0, v65, vcc
	v_add_co_u32_e32 v64, vcc, 0xf003000, v64
	v_mov_b64_e32 v[198:199], v[66:67]
	v_mov_b64_e32 v[196:197], v[66:67]
	v_addc_co_u32_e32 v65, vcc, 0, v65, vcc
	v_mov_b64_e32 v[194:195], v[64:65]
	v_mov_b64_e32 v[192:193], v[64:65]
	v_lshlrev_b32_e32 v64, 4, v168
	s_nop 0
	v_mov_b32_e32 v64, s10
	ds_read_b32 v96, v64
	v_lshlrev_b32_e32 v178, 2, v168
	v_add_u32_e32 v178, 0x20b00, v178
	ds_read_b32 v184, v178
	ds_read_b32 v185, v178 offset:512
	ds_read_b32 v186, v178 offset:768
	ds_read_b32 v187, v178 offset:1024
	v_or_b32_e32 v64, s11, v215
	v_lshlrev_b32_e32 v68, 3, v218
	v_mul_u32_u24_e32 v69, 0x110, v215
	v_mad_u64_u32 v[64:65], s[12:13], v64, s93, v[208:209]
	v_add3_u32 v176, 0, v68, v69
	ds_read_b128 v[168:171], v64 offset:53248
	ds_read_b128 v[164:167], v64 offset:53280
	ds_read_b128 v[160:163], v64 offset:53312
	ds_read_b128 v[156:159], v64 offset:53344
	v_add_u32_e32 v177, 0x2000, v176
	s_add_i32 s12, 0, 0x20b00
	v_add_u32_e32 v220, s12, v217
	v_add_u32_e32 v219, s15, v217
	s_add_i32 s13, 0, 0x20d00
	s_add_i32 s15, 0, 0x20e00
	s_add_i32 s42, 0, 0x20f00
	s_movk_i32 s43, 0x840
	v_or_b32_e32 v216, 32, v215
	ds_read2_b64 v[232:235], v176 offset0:0 offset1:2
	ds_read2_b64 v[236:239], v177 offset0:64 offset1:66
	ds_read2_b64 v[240:243], v176 offset0:4 offset1:6
	ds_read2_b64 v[180:183], v177 offset0:68 offset1:70
	v_cvt_pk_bf16_f32 v172, v0, v1
	v_cvt_pk_bf16_f32 v173, v2, v3
	v_cvt_pk_bf16_f32 v174, v4, v5
	v_cvt_pk_bf16_f32 v175, v6, v7
	s_nop 0
	s_waitcnt lgkmcnt(3)
	v_mfma_f32_32x32x16_bf16 v[80:95], v[232:235], v[172:175], 0
	v_fma_f32 v184, v184, v185, v186
	v_max_f32_e32 v187, v187, v187
	v_max_f32_e64 v184, |v184|, v187
	v_rcp_f32_e32 v184, v184
	s_nop 1
	ds_write_b32 v178, v184 offset:8960
	ds_read2_b64 v[232:235], v176 offset0:8 offset1:10
	s_waitcnt lgkmcnt(3)
	v_mfma_f32_32x32x16_bf16 v[64:79], v[236:239], v[172:175], 0
	ds_read2_b64 v[236:239], v177 offset0:72 offset1:74
	v_cvt_pk_bf16_f32 v244, v8, v9
	v_cvt_pk_bf16_f32 v245, v10, v11
	v_cvt_pk_bf16_f32 v246, v12, v13
	v_cvt_pk_bf16_f32 v247, v14, v15
	v_pk_mul_f32 v[0:1], v[0:1], v[96:97] op_sel_hi:[1,0]
	v_pk_mul_f32 v[2:3], v[2:3], v[96:97] op_sel_hi:[1,0]
	v_pk_mul_f32 v[4:5], v[4:5], v[96:97] op_sel_hi:[1,0]
	v_pk_mul_f32 v[6:7], v[6:7], v[96:97] op_sel_hi:[1,0]
	s_waitcnt lgkmcnt(3)
	v_mfma_f32_32x32x16_bf16 v[80:95], v[240:243], v[244:247], v[80:95]
	ds_read2_b64 v[240:243], v176 offset0:12 offset1:14
	s_waitcnt lgkmcnt(3)
	v_mfma_f32_32x32x16_bf16 v[64:79], v[180:183], v[244:247], v[64:79]
	ds_read2_b64 v[180:183], v177 offset0:76 offset1:78
	global_load_dwordx2 v[206:207], v[206:207], off sc1
	v_cvt_pk_bf16_f32 v172, v16, v17
	v_cvt_pk_bf16_f32 v173, v18, v19
	v_cvt_pk_bf16_f32 v174, v20, v21
	v_cvt_pk_bf16_f32 v175, v22, v23
	v_pk_mul_f32 v[8:9], v[8:9], v[96:97] op_sel_hi:[1,0]
	v_pk_mul_f32 v[10:11], v[10:11], v[96:97] op_sel_hi:[1,0]
	v_pk_mul_f32 v[12:13], v[12:13], v[96:97] op_sel_hi:[1,0]
	v_pk_mul_f32 v[14:15], v[14:15], v[96:97] op_sel_hi:[1,0]
	s_waitcnt lgkmcnt(3)
	v_mfma_f32_32x32x16_bf16 v[80:95], v[232:235], v[172:175], v[80:95]
	ds_read2_b64 v[232:235], v176 offset0:16 offset1:18
	s_waitcnt lgkmcnt(3)
	v_mfma_f32_32x32x16_bf16 v[64:79], v[236:239], v[172:175], v[64:79]
	ds_read2_b64 v[236:239], v177 offset0:80 offset1:82
	v_cvt_pk_bf16_f32 v244, v24, v25
	v_cvt_pk_bf16_f32 v245, v26, v27
	v_cvt_pk_bf16_f32 v246, v28, v29
	v_cvt_pk_bf16_f32 v247, v30, v31
	v_pk_mul_f32 v[16:17], v[16:17], v[96:97] op_sel_hi:[1,0]
	v_pk_mul_f32 v[18:19], v[18:19], v[96:97] op_sel_hi:[1,0]
	v_pk_mul_f32 v[20:21], v[20:21], v[96:97] op_sel_hi:[1,0]
	v_pk_mul_f32 v[22:23], v[22:23], v[96:97] op_sel_hi:[1,0]
	s_waitcnt lgkmcnt(3)
	v_mfma_f32_32x32x16_bf16 v[80:95], v[240:243], v[244:247], v[80:95]
	ds_read2_b64 v[240:243], v176 offset0:20 offset1:22
	s_waitcnt lgkmcnt(3)
	v_mfma_f32_32x32x16_bf16 v[64:79], v[180:183], v[244:247], v[64:79]
	ds_read2_b64 v[180:183], v177 offset0:84 offset1:86
	global_load_dwordx2 v[204:205], v[204:205], off offset:2048 sc1
	v_cvt_pk_bf16_f32 v172, v32, v33
	v_cvt_pk_bf16_f32 v173, v34, v35
	v_cvt_pk_bf16_f32 v174, v36, v37
	v_cvt_pk_bf16_f32 v175, v38, v39
	v_pk_mul_f32 v[24:25], v[24:25], v[96:97] op_sel_hi:[1,0]
	v_pk_mul_f32 v[26:27], v[26:27], v[96:97] op_sel_hi:[1,0]
	v_pk_mul_f32 v[28:29], v[28:29], v[96:97] op_sel_hi:[1,0]
	v_pk_mul_f32 v[30:31], v[30:31], v[96:97] op_sel_hi:[1,0]
	s_waitcnt lgkmcnt(3)
	v_mfma_f32_32x32x16_bf16 v[80:95], v[232:235], v[172:175], v[80:95]
	ds_read2_b64 v[232:235], v176 offset0:24 offset1:26
	s_waitcnt lgkmcnt(3)
	v_mfma_f32_32x32x16_bf16 v[64:79], v[236:239], v[172:175], v[64:79]
	ds_read2_b64 v[236:239], v177 offset0:88 offset1:90
	v_cvt_pk_bf16_f32 v244, v40, v41
	v_cvt_pk_bf16_f32 v245, v42, v43
	v_cvt_pk_bf16_f32 v246, v44, v45
	v_cvt_pk_bf16_f32 v247, v46, v47
	v_pk_mul_f32 v[32:33], v[32:33], v[96:97] op_sel_hi:[1,0]
	v_pk_mul_f32 v[34:35], v[34:35], v[96:97] op_sel_hi:[1,0]
	v_pk_mul_f32 v[36:37], v[36:37], v[96:97] op_sel_hi:[1,0]
	v_pk_mul_f32 v[38:39], v[38:39], v[96:97] op_sel_hi:[1,0]
	s_waitcnt lgkmcnt(3)
	v_mfma_f32_32x32x16_bf16 v[80:95], v[240:243], v[244:247], v[80:95]
	ds_read2_b64 v[240:243], v176 offset0:28 offset1:30
	s_waitcnt lgkmcnt(3)
	v_mfma_f32_32x32x16_bf16 v[64:79], v[180:183], v[244:247], v[64:79]
	ds_read2_b64 v[180:183], v177 offset0:92 offset1:94
	global_load_dwordx2 v[202:203], v[202:203], off sc1
	v_cvt_pk_bf16_f32 v172, v48, v49
	v_cvt_pk_bf16_f32 v173, v50, v51
	v_cvt_pk_bf16_f32 v174, v52, v53
	v_cvt_pk_bf16_f32 v175, v54, v55
	v_pk_mul_f32 v[40:41], v[40:41], v[96:97] op_sel_hi:[1,0]
	v_pk_mul_f32 v[42:43], v[42:43], v[96:97] op_sel_hi:[1,0]
	v_pk_mul_f32 v[44:45], v[44:45], v[96:97] op_sel_hi:[1,0]
	v_pk_mul_f32 v[46:47], v[46:47], v[96:97] op_sel_hi:[1,0]
	s_waitcnt lgkmcnt(3)
	v_mfma_f32_32x32x16_bf16 v[80:95], v[232:235], v[172:175], v[80:95]
	s_waitcnt lgkmcnt(2)
	v_mfma_f32_32x32x16_bf16 v[64:79], v[236:239], v[172:175], v[64:79]
	v_cvt_pk_bf16_f32 v244, v56, v57
	v_cvt_pk_bf16_f32 v245, v58, v59
	v_cvt_pk_bf16_f32 v246, v60, v61
	v_cvt_pk_bf16_f32 v247, v62, v63
	v_pk_mul_f32 v[48:49], v[48:49], v[96:97] op_sel_hi:[1,0]
	v_pk_mul_f32 v[50:51], v[50:51], v[96:97] op_sel_hi:[1,0]
	v_pk_mul_f32 v[52:53], v[52:53], v[96:97] op_sel_hi:[1,0]
	v_pk_mul_f32 v[54:55], v[54:55], v[96:97] op_sel_hi:[1,0]
	s_waitcnt lgkmcnt(1)
	v_mfma_f32_32x32x16_bf16 v[80:95], v[240:243], v[244:247], v[80:95]
	v_pk_mul_f32 v[56:57], v[56:57], v[96:97] op_sel_hi:[1,0]
	v_pk_mul_f32 v[58:59], v[58:59], v[96:97] op_sel_hi:[1,0]
	v_pk_mul_f32 v[60:61], v[60:61], v[96:97] op_sel_hi:[1,0]
	v_pk_mul_f32 v[62:63], v[62:63], v[96:97] op_sel_hi:[1,0]
	v_lshl_add_u32 v176, v215, 1, s2
	v_mad_u32_u24 v177, v215, s93, v219
	s_waitcnt lgkmcnt(0)
	v_mfma_f32_32x32x16_bf16 v[64:79], v[180:183], v[244:247], v[64:79]
	global_load_dwordx2 v[200:201], v[200:201], off offset:2048 sc1
	ds_read_b128 v[172:175], v220
	ds_read_b128 v[232:235], v220 offset:32
	ds_read_b128 v[236:239], v220 offset:64
	ds_read_b128 v[240:243], v220 offset:96
	s_waitcnt lgkmcnt(3)
	v_pk_mul_f32 v[82:83], v[82:83], v[174:175]
	s_waitcnt lgkmcnt(2)
	v_pk_mul_f32 v[86:87], v[86:87], v[234:235]
	s_waitcnt lgkmcnt(1)
	v_pk_mul_f32 v[90:91], v[90:91], v[238:239]
	v_pk_mul_f32 v[88:89], v[88:89], v[236:237]
	v_pk_mul_f32 v[84:85], v[84:85], v[232:233]
	ds_read_b128 v[232:235], v177
	ds_read_b128 v[236:239], v177 offset:32
	s_waitcnt lgkmcnt(2)
	v_pk_mul_f32 v[94:95], v[94:95], v[242:243]
	v_pk_mul_f32 v[92:93], v[92:93], v[240:241]
	v_pk_mul_f32 v[80:81], v[80:81], v[172:173]
	s_waitcnt lgkmcnt(1)
	s_nop 0
	v_mfma_f32_32x32x16_bf16 v[80:95], v[232:235], v[168:171], v[80:95]
	ds_read_b128 v[232:235], v177 offset:64
	s_waitcnt lgkmcnt(1)
	v_mfma_f32_32x32x16_bf16 v[80:95], v[236:239], v[164:167], v[80:95]
	s_waitcnt lgkmcnt(0)
	v_mfma_f32_32x32x16_bf16 v[80:95], v[232:235], v[160:163], v[80:95]
	ds_read_b128 v[232:235], v177 offset:96
	v_add_u32_e32 v177, s13, v217
	s_waitcnt lgkmcnt(0)
	v_mfma_f32_32x32x16_bf16 v[80:95], v[232:235], v[156:159], v[80:95]
	ds_read_b128 v[232:235], v220 offset:8960
	ds_read_b128 v[236:239], v220 offset:8992
	ds_read_b128 v[240:243], v220 offset:9024
	ds_read_b128 v[172:175], v220 offset:9056
	v_mad_u32_u24 v179, v218, s43, v176
	s_cmpk_eq_i32 s82, 0x7c0
	s_cbranch_scc1 .Lmls_3
	buffer_load_dwordx4 v[128:131], v128, s[76:79], 0 offen sc1
.Lmls_3:
	s_nop 7
	s_nop 3
	s_waitcnt lgkmcnt(0)
	v_pk_mul_f32 v[184:185], v[80:81], v[232:233]
	v_pk_mul_f32 v[186:187], v[82:83], v[234:235]
	v_cvt_pk_bf16_f32 v184, v184, v185
	v_cvt_pk_bf16_f32 v186, v186, v187
	ds_write_b16 v179, v184
	ds_write_b16_d16_hi v179, v184 offset:528
	ds_write_b16 v179, v186 offset:1056
	ds_write_b16_d16_hi v179, v186 offset:1584
	global_load_dwordx2 v[198:199], v[198:199], off sc1
	v_pk_mul_f32 v[184:185], v[84:85], v[236:237]
	v_pk_mul_f32 v[186:187], v[86:87], v[238:239]
	v_cvt_pk_bf16_f32 v184, v184, v185
	v_cvt_pk_bf16_f32 v186, v186, v187
	ds_write_b16 v179, v184 offset:4224
	ds_write_b16_d16_hi v179, v184 offset:4752
	ds_write_b16 v179, v186 offset:5280
	ds_write_b16_d16_hi v179, v186 offset:5808
	s_cmpk_eq_i32 s82, 0x7c0
	s_cbranch_scc1 .Lmls_4
	buffer_load_dwordx4 v[140:143], v140, s[76:79], 0 offen sc1
.Lmls_4:
	v_pk_mul_f32 v[184:185], v[88:89], v[240:241]
	v_pk_mul_f32 v[186:187], v[90:91], v[242:243]
	v_cvt_pk_bf16_f32 v184, v184, v185
	v_cvt_pk_bf16_f32 v186, v186, v187
	ds_write_b16 v179, v184 offset:8448
	ds_write_b16_d16_hi v179, v184 offset:8976
	ds_write_b16 v179, v186 offset:9504
	ds_write_b16_d16_hi v179, v186 offset:10032
	global_load_dwordx2 v[196:197], v[196:197], off offset:2048 sc1
	v_pk_mul_f32 v[184:185], v[92:93], v[172:173]
	v_pk_mul_f32 v[186:187], v[94:95], v[174:175]
	v_cvt_pk_bf16_f32 v184, v184, v185
	v_cvt_pk_bf16_f32 v186, v186, v187
	ds_write_b16 v179, v184 offset:12672
	ds_write_b16_d16_hi v179, v184 offset:13200
	ds_write_b16 v179, v186 offset:13728
	ds_write_b16_d16_hi v179, v186 offset:14256
	s_cmpk_eq_i32 s82, 0x7c0
	s_cbranch_scc1 .Lmls_5
	buffer_load_dwordx4 v[144:147], v144, s[76:79], 0 offen sc1
.Lmls_5:
	v_mad_u32_u24 v94, v216, s93, v219
	ds_read_b128 v[82:85], v220 offset:128
	ds_read_b128 v[86:89], v220 offset:160
	ds_read_b128 v[90:93], v220 offset:192
	ds_read_b128 v[172:175], v220 offset:224
	s_waitcnt lgkmcnt(3)
	v_pk_mul_f32 v[66:67], v[66:67], v[84:85]
	s_waitcnt lgkmcnt(2)
	v_pk_mul_f32 v[68:69], v[68:69], v[86:87]
	s_waitcnt lgkmcnt(1)
	v_pk_mul_f32 v[72:73], v[72:73], v[90:91]
	v_pk_mul_f32 v[74:75], v[74:75], v[92:93]
	v_pk_mul_f32 v[70:71], v[70:71], v[88:89]
	ds_read_b128 v[86:89], v94
	ds_read_b128 v[90:93], v94 offset:32
	s_waitcnt lgkmcnt(2)
	v_pk_mul_f32 v[76:77], v[76:77], v[172:173]
	v_pk_mul_f32 v[78:79], v[78:79], v[174:175]
	v_pk_mul_f32 v[64:65], v[64:65], v[82:83]
	s_waitcnt lgkmcnt(1)
	s_nop 0
	v_mfma_f32_32x32x16_bf16 v[64:79], v[86:89], v[168:171], v[64:79]
	ds_read_b128 v[86:89], v94 offset:64
	s_waitcnt lgkmcnt(1)
	v_mfma_f32_32x32x16_bf16 v[64:79], v[90:93], v[164:167], v[64:79]
	s_waitcnt lgkmcnt(0)
	v_mfma_f32_32x32x16_bf16 v[64:79], v[86:89], v[160:163], v[64:79]
	ds_read_b128 v[86:89], v94 offset:96
	s_waitcnt lgkmcnt(0)
	v_mfma_f32_32x32x16_bf16 v[64:79], v[86:89], v[156:159], v[64:79]
	ds_read_b128 v[232:235], v220 offset:9088
	ds_read_b128 v[236:239], v220 offset:9120
	ds_read_b128 v[240:243], v220 offset:9152
	ds_read_b128 v[172:175], v220 offset:9184
	global_load_dwordx2 v[194:195], v[194:195], off sc1
	s_nop 7
	s_nop 4
	s_waitcnt lgkmcnt(0)
	v_pk_mul_f32 v[184:185], v[64:65], v[232:233]
	v_pk_mul_f32 v[186:187], v[66:67], v[234:235]
	v_cvt_pk_bf16_f32 v184, v184, v185
	v_cvt_pk_bf16_f32 v186, v186, v187
	ds_write_b16 v179, v184 offset:16896
	ds_write_b16_d16_hi v179, v184 offset:17424
	ds_write_b16 v179, v186 offset:17952
	ds_write_b16_d16_hi v179, v186 offset:18480
	s_cmpk_eq_i32 s82, 0x7c0
	s_cbranch_scc1 .Lmls_6
	buffer_load_dwordx4 v[148:151], v148, s[76:79], 0 offen sc1
.Lmls_6:
	v_pk_mul_f32 v[184:185], v[68:69], v[236:237]
	v_pk_mul_f32 v[186:187], v[70:71], v[238:239]
	v_cvt_pk_bf16_f32 v184, v184, v185
	v_cvt_pk_bf16_f32 v186, v186, v187
	ds_write_b16 v179, v184 offset:21120
	ds_write_b16_d16_hi v179, v184 offset:21648
	ds_write_b16 v179, v186 offset:22176
	ds_write_b16_d16_hi v179, v186 offset:22704
	global_load_dwordx2 v[192:193], v[192:193], off offset:2048 sc1
	v_pk_mul_f32 v[184:185], v[72:73], v[240:241]
	v_pk_mul_f32 v[186:187], v[74:75], v[242:243]
	v_cvt_pk_bf16_f32 v184, v184, v185
	v_cvt_pk_bf16_f32 v186, v186, v187
	ds_write_b16 v179, v184 offset:25344
	ds_write_b16_d16_hi v179, v184 offset:25872
	ds_write_b16 v179, v186 offset:26400
	ds_write_b16_d16_hi v179, v186 offset:26928
	v_pk_mul_f32 v[184:185], v[76:77], v[172:173]
	v_pk_mul_f32 v[186:187], v[78:79], v[174:175]
	v_cvt_pk_bf16_f32 v184, v184, v185
	v_cvt_pk_bf16_f32 v186, v186, v187
	ds_write_b16 v179, v184 offset:29568
	ds_write_b16_d16_hi v179, v184 offset:30096
	ds_write_b16 v179, v186 offset:30624
	ds_write_b16_d16_hi v179, v186 offset:31152
	v_mad_u32_u24 v72, v215, s93, v208
	v_mad_u32_u24 v73, v216, s93, v208
	v_and_b32_e32 v74, 3, v214
	v_cmp_eq_u32_e32 vcc, 0, v74
	ds_read_b128 v[64:67], v72 offset:34816
	ds_read_b128 v[68:71], v72 offset:34848
	ds_read_b128 v[76:79], v72 offset:34880
	ds_read_b128 v[80:83], v72 offset:34912
	ds_read_b128 v[84:87], v73 offset:34816
	ds_read_b128 v[88:91], v73 offset:34848
	s_waitcnt lgkmcnt(5)
	v_mfma_f32_32x32x16_bf16 v[0:15], v[64:67], v[168:171], v[0:15]
	ds_read_b128 v[64:67], v73 offset:34880
	s_waitcnt lgkmcnt(5)
	v_mfma_f32_32x32x16_bf16 v[0:15], v[68:71], v[164:167], v[0:15]
	ds_read_b128 v[68:71], v73 offset:34912
	s_waitcnt lgkmcnt(5)
	v_mfma_f32_32x32x16_bf16 v[0:15], v[76:79], v[160:163], v[0:15]
	ds_read_b128 v[76:79], v72 offset:44032
	s_waitcnt lgkmcnt(5)
	v_mfma_f32_32x32x16_bf16 v[0:15], v[80:83], v[156:159], v[0:15]
	ds_read_b128 v[80:83], v72 offset:44064
	s_waitcnt lgkmcnt(5)
	v_mfma_f32_32x32x16_bf16 v[16:31], v[84:87], v[168:171], v[16:31]
	ds_read_b128 v[84:87], v72 offset:44096
	s_waitcnt lgkmcnt(5)
	v_mfma_f32_32x32x16_bf16 v[16:31], v[88:91], v[164:167], v[16:31]
	ds_read_b128 v[88:91], v72 offset:44128
	s_waitcnt lgkmcnt(5)
	v_mfma_f32_32x32x16_bf16 v[16:31], v[64:67], v[160:163], v[16:31]
	ds_read_b128 v[64:67], v72 offset:48640
	s_waitcnt lgkmcnt(5)
	v_mfma_f32_32x32x16_bf16 v[16:31], v[68:71], v[156:159], v[16:31]
	ds_read_b128 v[68:71], v72 offset:48672
	s_waitcnt lgkmcnt(5)
	v_mfma_f32_32x32x16_bf16 v[32:47], v[76:79], v[168:171], v[32:47]
	ds_read_b128 v[76:79], v72 offset:48704
	s_waitcnt lgkmcnt(5)
	v_mfma_f32_32x32x16_bf16 v[32:47], v[80:83], v[164:167], v[32:47]
	ds_read_b128 v[80:83], v72 offset:48736
	s_waitcnt lgkmcnt(5)
	v_mfma_f32_32x32x16_bf16 v[32:47], v[84:87], v[160:163], v[32:47]
	s_waitcnt lgkmcnt(4)
	v_mfma_f32_32x32x16_bf16 v[32:47], v[88:91], v[156:159], v[32:47]
	s_waitcnt lgkmcnt(3)
	v_mfma_f32_32x32x16_bf16 v[48:63], v[64:67], v[168:171], v[48:63]
	s_waitcnt lgkmcnt(2)
	v_mfma_f32_32x32x16_bf16 v[48:63], v[68:71], v[164:167], v[48:63]
	s_waitcnt lgkmcnt(1)
	v_mfma_f32_32x32x16_bf16 v[48:63], v[76:79], v[160:163], v[48:63]
	s_waitcnt lgkmcnt(0)
	v_mfma_f32_32x32x16_bf16 v[48:63], v[80:83], v[156:159], v[48:63]
	v_ashrrev_i32_e32 v64, 2, v214
	v_mul_lo_u32 v65, v64, s93
	v_lshlrev_b32_e32 v66, 5, v74
	v_add3_u32 v65, 0, v65, v66
	ds_read_b128 v[66:69], v65 offset:34816
	ds_read_b128 v[70:73], v65 offset:34832
	s_waitcnt lgkmcnt(1)
	v_lshlrev_b32_e32 v65, 16, v66
	v_and_b32_e32 v66, 0xffff0000, v66
	v_add_f32_e32 v65, v65, v66
	s_waitcnt lgkmcnt(0)
	v_lshlrev_b32_e32 v66, 16, v70
	v_and_b32_e32 v70, 0xffff0000, v70
	v_add_f32_e32 v66, v66, v70
	v_add_f32_e32 v65, v65, v66
	v_lshlrev_b32_e32 v66, 16, v67
	v_and_b32_e32 v67, 0xffff0000, v67
	v_add_f32_e32 v66, v66, v67
	v_lshlrev_b32_e32 v67, 16, v71
	v_and_b32_e32 v70, 0xffff0000, v71
	v_add_f32_e32 v67, v67, v70
	v_add_f32_e32 v65, 0, v65
	v_add_f32_e32 v66, v66, v67
	v_add_f32_e32 v65, v66, v65
	v_lshlrev_b32_e32 v66, 16, v68
	v_and_b32_e32 v67, 0xffff0000, v68
	v_add_f32_e32 v66, v66, v67
	v_lshlrev_b32_e32 v67, 16, v72
	v_and_b32_e32 v68, 0xffff0000, v72
	v_add_f32_e32 v67, v67, v68
	v_add_f32_e32 v66, v66, v67
	v_add_f32_e32 v65, v66, v65
	v_lshlrev_b32_e32 v66, 16, v69
	v_and_b32_e32 v67, 0xffff0000, v69
	v_add_f32_e32 v66, v66, v67
	v_lshlrev_b32_e32 v67, 16, v73
	v_and_b32_e32 v68, 0xffff0000, v73
	v_add_f32_e32 v67, v67, v68
	v_add_f32_e32 v66, v66, v67
	v_add_f32_e32 v65, v66, v65
	ds_bpermute_b32 v66, v189, v65
	s_waitcnt lgkmcnt(0)
	v_add_f32_e32 v65, v65, v66
	ds_bpermute_b32 v66, v191, v65
	s_and_saveexec_b64 s[12:13], vcc
	s_cbranch_execz .LBB0_206
	v_lshl_add_u32 v64, v64, 2, 0
	v_add_u32_e32 v64, 0x21000, v64
	s_waitcnt lgkmcnt(0)
	v_add_f32_e32 v65, v65, v66
	ds_read_b32 v66, v64
	s_waitcnt lgkmcnt(0)
	v_fmac_f32_e32 v65, v96, v66
	ds_write_b32 v64, v65
	s_branch .LBB0_206
